# PEER step-A top-16 insertion network rewritten with v_med3_u32 (16 independent ops per key instead of 32 dependent max/min), bit-identical
# speedup vs baseline: 1.1995x; 1.0058x over previous
; DEV float lo2f(u32 w) { return __uint_as_float(w << 16); }
; DEV float hi2f(u32 w) { return __uint_as_float(w & 0xffff0000u); }
; #define MONO_KEY(v_, m_, t_) mono_key((v_), (m_), (t_))
; DEV u32 mono_key(float v, u32 mask, int tag) {
;   u32 u = __float_as_uint(v);
;   u32 k = (u & 0x80000000u) ? ~u : (u | 0x80000000u);
;   return (k & ~mask) | (u32)tag;
; }
; DEV float key_value(u32 k, u32 mask) {
;   k &= ~mask;
;   u32 u = (k & 0x80000000u) ? (k & 0x7fffffffu) : ~k;
;   return __uint_as_float(u);
; }
; __device__ __forceinline__ void ph_peer(const P& p, int l, int nrows, char* smem, int dryc) {
;     ...
; #pragma unroll
;         for (int q = 0; q < 4; q++) {
;           const int c = c0 + q;
;           const u32x4 sv = cur[q];
; #pragma unroll
;           for (int e = 0; e < 4; e++) {
;             KEY_INSERT(MONO_KEY(lo2f(sv[e]), 127u, 127 - (c * 8 + e * 2 + 0)));
;             KEY_INSERT(MONO_KEY(hi2f(sv[e]), 127u, 127 - (c * 8 + e * 2 + 1)));
;           }
;         }
.LBB0_652:
	v_lshl_add_u64 v[32:33], v[32:33], 0, 64
	v_lshlrev_b32_e32 v50, 16, v28
	v_ashrrev_i32_e32 v51, 31, v50
	v_or_b32_e32 v51, 0x80000000, v51
	v_xor_b32_e32 v52, v50, v51
	v_and_b32_e32 v52, 0xffffff80, v52
	v_add3_u32 v52, s1, v52, 31
	v_med3_u32 v34, v35, v34, v52
	v_med3_u32 v35, v36, v35, v52
	v_med3_u32 v36, v37, v36, v52
	v_med3_u32 v37, v38, v37, v52
	v_med3_u32 v38, v39, v38, v52
	v_med3_u32 v39, v40, v39, v52
	v_med3_u32 v40, v41, v40, v52
	v_med3_u32 v41, v42, v41, v52
	v_med3_u32 v42, v43, v42, v52
	v_med3_u32 v43, v44, v43, v52
	v_med3_u32 v44, v45, v44, v52
	v_med3_u32 v45, v46, v45, v52
	v_med3_u32 v46, v48, v46, v52
	v_med3_u32 v48, v49, v48, v52
	v_med3_u32 v49, v47, v49, v52
	v_max_u32_e32 v47, v47, v52
	v_and_b32_e32 v50, 0xffff0000, v28
	v_ashrrev_i32_e32 v51, 31, v50
	v_or_b32_e32 v51, 0x80000000, v51
	v_xor_b32_e32 v52, v50, v51
	v_and_b32_e32 v52, 0xffffff80, v52
	v_add3_u32 v52, s1, v52, 30
	v_med3_u32 v34, v35, v34, v52
	v_med3_u32 v35, v36, v35, v52
	v_med3_u32 v36, v37, v36, v52
	v_med3_u32 v37, v38, v37, v52
	v_med3_u32 v38, v39, v38, v52
	v_med3_u32 v39, v40, v39, v52
	v_med3_u32 v40, v41, v40, v52
	v_med3_u32 v41, v42, v41, v52
	v_med3_u32 v42, v43, v42, v52
	v_med3_u32 v43, v44, v43, v52
	v_med3_u32 v44, v45, v44, v52
	v_med3_u32 v45, v46, v45, v52
	v_med3_u32 v46, v48, v46, v52
	v_med3_u32 v48, v49, v48, v52
	v_med3_u32 v49, v47, v49, v52
	v_max_u32_e32 v47, v47, v52
	v_lshlrev_b32_e32 v50, 16, v29
	v_ashrrev_i32_e32 v51, 31, v50
	v_or_b32_e32 v51, 0x80000000, v51
	v_xor_b32_e32 v52, v50, v51
	v_and_b32_e32 v52, 0xffffff80, v52
	v_add3_u32 v52, s1, v52, 29
	v_med3_u32 v34, v35, v34, v52
	v_med3_u32 v35, v36, v35, v52
	v_med3_u32 v36, v37, v36, v52
	v_med3_u32 v37, v38, v37, v52
	v_med3_u32 v38, v39, v38, v52
	v_med3_u32 v39, v40, v39, v52
	v_med3_u32 v40, v41, v40, v52
	v_med3_u32 v41, v42, v41, v52
	v_med3_u32 v42, v43, v42, v52
	v_med3_u32 v43, v44, v43, v52
	v_med3_u32 v44, v45, v44, v52
	v_med3_u32 v45, v46, v45, v52
	v_med3_u32 v46, v48, v46, v52
	v_med3_u32 v48, v49, v48, v52
	v_med3_u32 v49, v47, v49, v52
	v_max_u32_e32 v47, v47, v52
	v_and_b32_e32 v50, 0xffff0000, v29
	v_ashrrev_i32_e32 v51, 31, v50
	v_or_b32_e32 v51, 0x80000000, v51
	v_xor_b32_e32 v52, v50, v51
	v_and_b32_e32 v52, 0xffffff80, v52
	v_add3_u32 v52, s1, v52, 28
	v_med3_u32 v34, v35, v34, v52
	v_med3_u32 v35, v36, v35, v52
	v_med3_u32 v36, v37, v36, v52
	v_med3_u32 v37, v38, v37, v52
	v_med3_u32 v38, v39, v38, v52
	v_med3_u32 v39, v40, v39, v52
	v_med3_u32 v40, v41, v40, v52
	v_med3_u32 v41, v42, v41, v52
	v_med3_u32 v42, v43, v42, v52
	v_med3_u32 v43, v44, v43, v52
	v_med3_u32 v44, v45, v44, v52
	v_med3_u32 v45, v46, v45, v52
	v_med3_u32 v46, v48, v46, v52
	v_med3_u32 v48, v49, v48, v52
	v_med3_u32 v49, v47, v49, v52
	v_max_u32_e32 v47, v47, v52
	v_lshlrev_b32_e32 v50, 16, v30
	v_ashrrev_i32_e32 v51, 31, v50
	v_or_b32_e32 v51, 0x80000000, v51
	v_xor_b32_e32 v52, v50, v51
	v_and_b32_e32 v52, 0xffffff80, v52
	v_add3_u32 v52, s1, v52, 27
	v_med3_u32 v34, v35, v34, v52
	v_med3_u32 v35, v36, v35, v52
	v_med3_u32 v36, v37, v36, v52
	v_med3_u32 v37, v38, v37, v52
	v_med3_u32 v38, v39, v38, v52
	v_med3_u32 v39, v40, v39, v52
	v_med3_u32 v40, v41, v40, v52
	v_med3_u32 v41, v42, v41, v52
	v_med3_u32 v42, v43, v42, v52
	v_med3_u32 v43, v44, v43, v52
	v_med3_u32 v44, v45, v44, v52
	v_med3_u32 v45, v46, v45, v52
	v_med3_u32 v46, v48, v46, v52
	v_med3_u32 v48, v49, v48, v52
	v_med3_u32 v49, v47, v49, v52
	v_max_u32_e32 v47, v47, v52
	v_and_b32_e32 v50, 0xffff0000, v30
	v_ashrrev_i32_e32 v51, 31, v50
	v_or_b32_e32 v51, 0x80000000, v51
	v_xor_b32_e32 v52, v50, v51
	v_and_b32_e32 v52, 0xffffff80, v52
	v_add3_u32 v52, s1, v52, 26
	v_med3_u32 v34, v35, v34, v52
	v_med3_u32 v35, v36, v35, v52
	v_med3_u32 v36, v37, v36, v52
	v_med3_u32 v37, v38, v37, v52
	v_med3_u32 v38, v39, v38, v52
	v_med3_u32 v39, v40, v39, v52
	v_med3_u32 v40, v41, v40, v52
	v_med3_u32 v41, v42, v41, v52
	v_med3_u32 v42, v43, v42, v52
	v_med3_u32 v43, v44, v43, v52
	v_med3_u32 v44, v45, v44, v52
	v_med3_u32 v45, v46, v45, v52
	v_med3_u32 v46, v48, v46, v52
	v_med3_u32 v48, v49, v48, v52
	v_med3_u32 v49, v47, v49, v52
	v_max_u32_e32 v47, v47, v52
	v_lshlrev_b32_e32 v50, 16, v31
	v_ashrrev_i32_e32 v51, 31, v50
	v_or_b32_e32 v51, 0x80000000, v51
	v_xor_b32_e32 v52, v50, v51
	v_and_b32_e32 v52, 0xffffff80, v52
	v_add3_u32 v52, s1, v52, 25
	v_med3_u32 v34, v35, v34, v52
	v_med3_u32 v35, v36, v35, v52
	v_med3_u32 v36, v37, v36, v52
	v_med3_u32 v37, v38, v37, v52
	v_med3_u32 v38, v39, v38, v52
	v_med3_u32 v39, v40, v39, v52
	v_med3_u32 v40, v41, v40, v52
	v_med3_u32 v41, v42, v41, v52
	v_med3_u32 v42, v43, v42, v52
	v_med3_u32 v43, v44, v43, v52
	v_med3_u32 v44, v45, v44, v52
	v_med3_u32 v45, v46, v45, v52
	v_med3_u32 v46, v48, v46, v52
	v_med3_u32 v48, v49, v48, v52
	v_med3_u32 v49, v47, v49, v52
	v_max_u32_e32 v47, v47, v52
	v_and_b32_e32 v50, 0xffff0000, v31
	v_ashrrev_i32_e32 v51, 31, v50
	v_or_b32_e32 v51, 0x80000000, v51
	v_xor_b32_e32 v52, v50, v51
	v_and_b32_e32 v52, 0xffffff80, v52
	v_add3_u32 v52, s1, v52, 24
	v_med3_u32 v34, v35, v34, v52
	v_med3_u32 v35, v36, v35, v52
	v_med3_u32 v36, v37, v36, v52
	v_med3_u32 v37, v38, v37, v52
	v_med3_u32 v38, v39, v38, v52
	v_med3_u32 v39, v40, v39, v52
	v_med3_u32 v40, v41, v40, v52
	v_med3_u32 v41, v42, v41, v52
	v_med3_u32 v42, v43, v42, v52
	v_med3_u32 v43, v44, v43, v52
	v_med3_u32 v44, v45, v44, v52
	v_med3_u32 v45, v46, v45, v52
	v_med3_u32 v46, v48, v46, v52
	v_med3_u32 v48, v49, v48, v52
	v_med3_u32 v49, v47, v49, v52
	v_max_u32_e32 v47, v47, v52
	v_lshlrev_b32_e32 v50, 16, v24
	v_ashrrev_i32_e32 v51, 31, v50
; DEV float lo2f(u32 w) { return __uint_as_float(w << 16); }
; DEV float hi2f(u32 w) { return __uint_as_float(w & 0xffff0000u); }
; #define MONO_KEY(v_, m_, t_) mono_key((v_), (m_), (t_))
; DEV u32 mono_key(float v, u32 mask, int tag) {
;   u32 u = __float_as_uint(v);
;   u32 k = (u & 0x80000000u) ? ~u : (u | 0x80000000u);
;   return (k & ~mask) | (u32)tag;
; }
; DEV float key_value(u32 k, u32 mask) {
;   k &= ~mask;
;   u32 u = (k & 0x80000000u) ? (k & 0x7fffffffu) : ~k;
;   return __uint_as_float(u);
; }
; __device__ __forceinline__ void ph_peer(const P& p, int l, int nrows, char* smem, int dryc) {
;     ...
; #pragma unroll
;         for (int q = 0; q < 4; q++) {
;           const int c = c0 + q;
;           const u32x4 sv = cur[q];
; #pragma unroll
;           for (int e = 0; e < 4; e++) {
;             KEY_INSERT(MONO_KEY(lo2f(sv[e]), 127u, 127 - (c * 8 + e * 2 + 0)));
;             KEY_INSERT(MONO_KEY(hi2f(sv[e]), 127u, 127 - (c * 8 + e * 2 + 1)));
;           }
;         }
	v_or_b32_e32 v51, 0x80000000, v51
	v_xor_b32_e32 v52, v50, v51
	v_and_b32_e32 v52, 0xffffff80, v52
	v_add3_u32 v52, s1, v52, 23
	v_med3_u32 v34, v35, v34, v52
	v_med3_u32 v35, v36, v35, v52
	v_med3_u32 v36, v37, v36, v52
	v_med3_u32 v37, v38, v37, v52
	v_med3_u32 v38, v39, v38, v52
	v_med3_u32 v39, v40, v39, v52
	v_med3_u32 v40, v41, v40, v52
	v_med3_u32 v41, v42, v41, v52
	v_med3_u32 v42, v43, v42, v52
	v_med3_u32 v43, v44, v43, v52
	v_med3_u32 v44, v45, v44, v52
	v_med3_u32 v45, v46, v45, v52
	v_med3_u32 v46, v48, v46, v52
	v_med3_u32 v48, v49, v48, v52
	v_med3_u32 v49, v47, v49, v52
	v_max_u32_e32 v47, v47, v52
	v_and_b32_e32 v50, 0xffff0000, v24
	v_ashrrev_i32_e32 v51, 31, v50
	v_or_b32_e32 v51, 0x80000000, v51
	v_xor_b32_e32 v52, v50, v51
	v_and_b32_e32 v52, 0xffffff80, v52
	v_add3_u32 v52, s1, v52, 22
	v_med3_u32 v34, v35, v34, v52
	v_med3_u32 v35, v36, v35, v52
	v_med3_u32 v36, v37, v36, v52
	v_med3_u32 v37, v38, v37, v52
	v_med3_u32 v38, v39, v38, v52
	v_med3_u32 v39, v40, v39, v52
	v_med3_u32 v40, v41, v40, v52
	v_med3_u32 v41, v42, v41, v52
	v_med3_u32 v42, v43, v42, v52
	v_med3_u32 v43, v44, v43, v52
	v_med3_u32 v44, v45, v44, v52
	v_med3_u32 v45, v46, v45, v52
	v_med3_u32 v46, v48, v46, v52
	v_med3_u32 v48, v49, v48, v52
	v_med3_u32 v49, v47, v49, v52
	v_max_u32_e32 v47, v47, v52
	v_lshlrev_b32_e32 v50, 16, v25
	v_ashrrev_i32_e32 v51, 31, v50
	v_or_b32_e32 v51, 0x80000000, v51
	v_xor_b32_e32 v52, v50, v51
	v_and_b32_e32 v52, 0xffffff80, v52
	v_add3_u32 v52, s1, v52, 21
	v_med3_u32 v34, v35, v34, v52
	v_med3_u32 v35, v36, v35, v52
	v_med3_u32 v36, v37, v36, v52
	v_med3_u32 v37, v38, v37, v52
	v_med3_u32 v38, v39, v38, v52
	v_med3_u32 v39, v40, v39, v52
	v_med3_u32 v40, v41, v40, v52
	v_med3_u32 v41, v42, v41, v52
	v_med3_u32 v42, v43, v42, v52
	v_med3_u32 v43, v44, v43, v52
	v_med3_u32 v44, v45, v44, v52
	v_med3_u32 v45, v46, v45, v52
	v_med3_u32 v46, v48, v46, v52
	v_med3_u32 v48, v49, v48, v52
	v_med3_u32 v49, v47, v49, v52
	v_max_u32_e32 v47, v47, v52
	v_and_b32_e32 v50, 0xffff0000, v25
	v_ashrrev_i32_e32 v51, 31, v50
	v_or_b32_e32 v51, 0x80000000, v51
	v_xor_b32_e32 v52, v50, v51
	v_and_b32_e32 v52, 0xffffff80, v52
	v_add3_u32 v52, s1, v52, 20
	v_med3_u32 v34, v35, v34, v52
	v_med3_u32 v35, v36, v35, v52
	v_med3_u32 v36, v37, v36, v52
	v_med3_u32 v37, v38, v37, v52
	v_med3_u32 v38, v39, v38, v52
	v_med3_u32 v39, v40, v39, v52
	v_med3_u32 v40, v41, v40, v52
	v_med3_u32 v41, v42, v41, v52
	v_med3_u32 v42, v43, v42, v52
	v_med3_u32 v43, v44, v43, v52
	v_med3_u32 v44, v45, v44, v52
	v_med3_u32 v45, v46, v45, v52
	v_med3_u32 v46, v48, v46, v52
	v_med3_u32 v48, v49, v48, v52
	v_med3_u32 v49, v47, v49, v52
	v_max_u32_e32 v47, v47, v52
	v_lshlrev_b32_e32 v50, 16, v26
	v_ashrrev_i32_e32 v51, 31, v50
	v_or_b32_e32 v51, 0x80000000, v51
	v_xor_b32_e32 v52, v50, v51
	v_and_b32_e32 v52, 0xffffff80, v52
	v_add3_u32 v52, s1, v52, 19
	v_med3_u32 v34, v35, v34, v52
	v_med3_u32 v35, v36, v35, v52
	v_med3_u32 v36, v37, v36, v52
	v_med3_u32 v37, v38, v37, v52
	v_med3_u32 v38, v39, v38, v52
	v_med3_u32 v39, v40, v39, v52
	v_med3_u32 v40, v41, v40, v52
	v_med3_u32 v41, v42, v41, v52
	v_med3_u32 v42, v43, v42, v52
	v_med3_u32 v43, v44, v43, v52
	v_med3_u32 v44, v45, v44, v52
	v_med3_u32 v45, v46, v45, v52
	v_med3_u32 v46, v48, v46, v52
	v_med3_u32 v48, v49, v48, v52
	v_med3_u32 v49, v47, v49, v52
	v_max_u32_e32 v47, v47, v52
	v_and_b32_e32 v50, 0xffff0000, v26
	v_ashrrev_i32_e32 v51, 31, v50
	v_or_b32_e32 v51, 0x80000000, v51
	v_xor_b32_e32 v52, v50, v51
	v_and_b32_e32 v52, 0xffffff80, v52
	v_add3_u32 v52, s1, v52, 18
	v_med3_u32 v34, v35, v34, v52
	v_med3_u32 v35, v36, v35, v52
	v_med3_u32 v36, v37, v36, v52
	v_med3_u32 v37, v38, v37, v52
	v_med3_u32 v38, v39, v38, v52
	v_med3_u32 v39, v40, v39, v52
	v_med3_u32 v40, v41, v40, v52
	v_med3_u32 v41, v42, v41, v52
	v_med3_u32 v42, v43, v42, v52
	v_med3_u32 v43, v44, v43, v52
	v_med3_u32 v44, v45, v44, v52
	v_med3_u32 v45, v46, v45, v52
	v_med3_u32 v46, v48, v46, v52
	v_med3_u32 v48, v49, v48, v52
	v_med3_u32 v49, v47, v49, v52
	v_max_u32_e32 v47, v47, v52
	v_lshlrev_b32_e32 v50, 16, v27
	v_ashrrev_i32_e32 v51, 31, v50
	v_or_b32_e32 v51, 0x80000000, v51
	v_xor_b32_e32 v52, v50, v51
	v_and_b32_e32 v52, 0xffffff80, v52
	v_add3_u32 v52, s1, v52, 17
	v_med3_u32 v34, v35, v34, v52
	v_med3_u32 v35, v36, v35, v52
	v_med3_u32 v36, v37, v36, v52
	v_med3_u32 v37, v38, v37, v52
	v_med3_u32 v38, v39, v38, v52
	v_med3_u32 v39, v40, v39, v52
	v_med3_u32 v40, v41, v40, v52
	v_med3_u32 v41, v42, v41, v52
	v_med3_u32 v42, v43, v42, v52
	v_med3_u32 v43, v44, v43, v52
	v_med3_u32 v44, v45, v44, v52
	v_med3_u32 v45, v46, v45, v52
	v_med3_u32 v46, v48, v46, v52
	v_med3_u32 v48, v49, v48, v52
	v_med3_u32 v49, v47, v49, v52
	v_max_u32_e32 v47, v47, v52
	v_and_b32_e32 v50, 0xffff0000, v27
	v_ashrrev_i32_e32 v51, 31, v50
	v_or_b32_e32 v51, 0x80000000, v51
	v_xor_b32_e32 v52, v50, v51
	v_and_b32_e32 v52, 0xffffff80, v52
	v_add3_u32 v52, s1, v52, 16
	v_med3_u32 v34, v35, v34, v52
	v_med3_u32 v35, v36, v35, v52
	v_med3_u32 v36, v37, v36, v52
	v_med3_u32 v37, v38, v37, v52
	v_med3_u32 v38, v39, v38, v52
	v_med3_u32 v39, v40, v39, v52
	v_med3_u32 v40, v41, v40, v52
	v_med3_u32 v41, v42, v41, v52
	v_med3_u32 v42, v43, v42, v52
	v_med3_u32 v43, v44, v43, v52
	v_med3_u32 v44, v45, v44, v52
	v_med3_u32 v45, v46, v45, v52
	v_med3_u32 v46, v48, v46, v52
	v_med3_u32 v48, v49, v48, v52
	v_med3_u32 v49, v47, v49, v52
	v_max_u32_e32 v47, v47, v52
	v_lshlrev_b32_e32 v50, 16, v20
	v_ashrrev_i32_e32 v51, 31, v50
	v_or_b32_e32 v51, 0x80000000, v51
	v_xor_b32_e32 v52, v50, v51
	v_and_b32_e32 v52, 0xffffff80, v52
	v_add3_u32 v52, s1, v52, 15
; DEV float lo2f(u32 w) { return __uint_as_float(w << 16); }
; DEV float hi2f(u32 w) { return __uint_as_float(w & 0xffff0000u); }
; #define MONO_KEY(v_, m_, t_) mono_key((v_), (m_), (t_))
; DEV u32 mono_key(float v, u32 mask, int tag) {
;   u32 u = __float_as_uint(v);
;   u32 k = (u & 0x80000000u) ? ~u : (u | 0x80000000u);
;   return (k & ~mask) | (u32)tag;
; }
; DEV float key_value(u32 k, u32 mask) {
;   k &= ~mask;
;   u32 u = (k & 0x80000000u) ? (k & 0x7fffffffu) : ~k;
;   return __uint_as_float(u);
; }
; __device__ __forceinline__ void ph_peer(const P& p, int l, int nrows, char* smem, int dryc) {
;     ...
; #pragma unroll
;         for (int q = 0; q < 4; q++) {
;           const int c = c0 + q;
;           const u32x4 sv = cur[q];
; #pragma unroll
;           for (int e = 0; e < 4; e++) {
;             KEY_INSERT(MONO_KEY(lo2f(sv[e]), 127u, 127 - (c * 8 + e * 2 + 0)));
;             KEY_INSERT(MONO_KEY(hi2f(sv[e]), 127u, 127 - (c * 8 + e * 2 + 1)));
;           }
;         }
	v_med3_u32 v34, v35, v34, v52
	v_med3_u32 v35, v36, v35, v52
	v_med3_u32 v36, v37, v36, v52
	v_med3_u32 v37, v38, v37, v52
	v_med3_u32 v38, v39, v38, v52
	v_med3_u32 v39, v40, v39, v52
	v_med3_u32 v40, v41, v40, v52
	v_med3_u32 v41, v42, v41, v52
	v_med3_u32 v42, v43, v42, v52
	v_med3_u32 v43, v44, v43, v52
	v_med3_u32 v44, v45, v44, v52
	v_med3_u32 v45, v46, v45, v52
	v_med3_u32 v46, v48, v46, v52
	v_med3_u32 v48, v49, v48, v52
	v_med3_u32 v49, v47, v49, v52
	v_max_u32_e32 v47, v47, v52
	v_and_b32_e32 v50, 0xffff0000, v20
	v_ashrrev_i32_e32 v51, 31, v50
	v_or_b32_e32 v51, 0x80000000, v51
	v_xor_b32_e32 v52, v50, v51
	v_and_b32_e32 v52, 0xffffff80, v52
	v_add3_u32 v52, s1, v52, 14
	v_med3_u32 v34, v35, v34, v52
	v_med3_u32 v35, v36, v35, v52
	v_med3_u32 v36, v37, v36, v52
	v_med3_u32 v37, v38, v37, v52
	v_med3_u32 v38, v39, v38, v52
	v_med3_u32 v39, v40, v39, v52
	v_med3_u32 v40, v41, v40, v52
	v_med3_u32 v41, v42, v41, v52
	v_med3_u32 v42, v43, v42, v52
	v_med3_u32 v43, v44, v43, v52
	v_med3_u32 v44, v45, v44, v52
	v_med3_u32 v45, v46, v45, v52
	v_med3_u32 v46, v48, v46, v52
	v_med3_u32 v48, v49, v48, v52
	v_med3_u32 v49, v47, v49, v52
	v_max_u32_e32 v47, v47, v52
	v_lshlrev_b32_e32 v50, 16, v21
	v_ashrrev_i32_e32 v51, 31, v50
	v_or_b32_e32 v51, 0x80000000, v51
	v_xor_b32_e32 v52, v50, v51
	v_and_b32_e32 v52, 0xffffff80, v52
	v_add3_u32 v52, s1, v52, 13
	v_med3_u32 v34, v35, v34, v52
	v_med3_u32 v35, v36, v35, v52
	v_med3_u32 v36, v37, v36, v52
	v_med3_u32 v37, v38, v37, v52
	v_med3_u32 v38, v39, v38, v52
	v_med3_u32 v39, v40, v39, v52
	v_med3_u32 v40, v41, v40, v52
	v_med3_u32 v41, v42, v41, v52
	v_med3_u32 v42, v43, v42, v52
	v_med3_u32 v43, v44, v43, v52
	v_med3_u32 v44, v45, v44, v52
	v_med3_u32 v45, v46, v45, v52
	v_med3_u32 v46, v48, v46, v52
	v_med3_u32 v48, v49, v48, v52
	v_med3_u32 v49, v47, v49, v52
	v_max_u32_e32 v47, v47, v52
	v_and_b32_e32 v50, 0xffff0000, v21
	v_ashrrev_i32_e32 v51, 31, v50
	v_or_b32_e32 v51, 0x80000000, v51
	v_xor_b32_e32 v52, v50, v51
	v_and_b32_e32 v52, 0xffffff80, v52
	v_add3_u32 v52, s1, v52, 12
	v_med3_u32 v34, v35, v34, v52
	v_med3_u32 v35, v36, v35, v52
	v_med3_u32 v36, v37, v36, v52
	v_med3_u32 v37, v38, v37, v52
	v_med3_u32 v38, v39, v38, v52
	v_med3_u32 v39, v40, v39, v52
	v_med3_u32 v40, v41, v40, v52
	v_med3_u32 v41, v42, v41, v52
	v_med3_u32 v42, v43, v42, v52
	v_med3_u32 v43, v44, v43, v52
	v_med3_u32 v44, v45, v44, v52
	v_med3_u32 v45, v46, v45, v52
	v_med3_u32 v46, v48, v46, v52
	v_med3_u32 v48, v49, v48, v52
	v_med3_u32 v49, v47, v49, v52
	v_max_u32_e32 v47, v47, v52
	v_lshlrev_b32_e32 v50, 16, v22
	v_ashrrev_i32_e32 v51, 31, v50
	v_or_b32_e32 v51, 0x80000000, v51
	v_xor_b32_e32 v52, v50, v51
	v_and_b32_e32 v52, 0xffffff80, v52
	v_add3_u32 v52, s1, v52, 11
	v_med3_u32 v34, v35, v34, v52
	v_med3_u32 v35, v36, v35, v52
	v_med3_u32 v36, v37, v36, v52
	v_med3_u32 v37, v38, v37, v52
	v_med3_u32 v38, v39, v38, v52
	v_med3_u32 v39, v40, v39, v52
	v_med3_u32 v40, v41, v40, v52
	v_med3_u32 v41, v42, v41, v52
	v_med3_u32 v42, v43, v42, v52
	v_med3_u32 v43, v44, v43, v52
	v_med3_u32 v44, v45, v44, v52
	v_med3_u32 v45, v46, v45, v52
	v_med3_u32 v46, v48, v46, v52
	v_med3_u32 v48, v49, v48, v52
	v_med3_u32 v49, v47, v49, v52
	v_max_u32_e32 v47, v47, v52
	v_and_b32_e32 v50, 0xffff0000, v22
	v_ashrrev_i32_e32 v51, 31, v50
	v_or_b32_e32 v51, 0x80000000, v51
	v_xor_b32_e32 v52, v50, v51
	v_and_b32_e32 v52, 0xffffff80, v52
	v_add3_u32 v52, s1, v52, 10
	v_med3_u32 v34, v35, v34, v52
	v_med3_u32 v35, v36, v35, v52
	v_med3_u32 v36, v37, v36, v52
	v_med3_u32 v37, v38, v37, v52
	v_med3_u32 v38, v39, v38, v52
	v_med3_u32 v39, v40, v39, v52
	v_med3_u32 v40, v41, v40, v52
	v_med3_u32 v41, v42, v41, v52
	v_med3_u32 v42, v43, v42, v52
	v_med3_u32 v43, v44, v43, v52
	v_med3_u32 v44, v45, v44, v52
	v_med3_u32 v45, v46, v45, v52
	v_med3_u32 v46, v48, v46, v52
	v_med3_u32 v48, v49, v48, v52
	v_med3_u32 v49, v47, v49, v52
	v_max_u32_e32 v47, v47, v52
	v_lshlrev_b32_e32 v50, 16, v23
	v_ashrrev_i32_e32 v51, 31, v50
	v_or_b32_e32 v51, 0x80000000, v51
	v_xor_b32_e32 v52, v50, v51
	v_and_b32_e32 v52, 0xffffff80, v52
	v_add3_u32 v52, s1, v52, 9
	v_med3_u32 v34, v35, v34, v52
	v_med3_u32 v35, v36, v35, v52
	v_med3_u32 v36, v37, v36, v52
	v_med3_u32 v37, v38, v37, v52
	v_med3_u32 v38, v39, v38, v52
	v_med3_u32 v39, v40, v39, v52
	v_med3_u32 v40, v41, v40, v52
	v_med3_u32 v41, v42, v41, v52
	v_med3_u32 v42, v43, v42, v52
	v_med3_u32 v43, v44, v43, v52
	v_med3_u32 v44, v45, v44, v52
	v_med3_u32 v45, v46, v45, v52
	v_med3_u32 v46, v48, v46, v52
	v_med3_u32 v48, v49, v48, v52
	v_med3_u32 v49, v47, v49, v52
	v_max_u32_e32 v47, v47, v52
	v_and_b32_e32 v50, 0xffff0000, v23
	v_ashrrev_i32_e32 v51, 31, v50
	v_or_b32_e32 v51, 0x80000000, v51
	v_xor_b32_e32 v52, v50, v51
	v_and_b32_e32 v52, 0xffffff80, v52
	v_add3_u32 v52, s1, v52, 8
	v_med3_u32 v34, v35, v34, v52
	v_med3_u32 v35, v36, v35, v52
	v_med3_u32 v36, v37, v36, v52
	v_med3_u32 v37, v38, v37, v52
	v_med3_u32 v38, v39, v38, v52
	v_med3_u32 v39, v40, v39, v52
	v_med3_u32 v40, v41, v40, v52
	v_med3_u32 v41, v42, v41, v52
	v_med3_u32 v42, v43, v42, v52
	v_med3_u32 v43, v44, v43, v52
	v_med3_u32 v44, v45, v44, v52
	v_med3_u32 v45, v46, v45, v52
	v_med3_u32 v46, v48, v46, v52
	v_med3_u32 v48, v49, v48, v52
	v_med3_u32 v49, v47, v49, v52
	v_max_u32_e32 v47, v47, v52
	v_lshlrev_b32_e32 v50, 16, v0
	v_ashrrev_i32_e32 v51, 31, v50
	v_or_b32_e32 v51, 0x80000000, v51
	v_xor_b32_e32 v52, v50, v51
	v_and_b32_e32 v52, 0xffffff80, v52
	v_add3_u32 v52, s1, v52, 7
	v_med3_u32 v34, v35, v34, v52
	v_med3_u32 v35, v36, v35, v52
	v_med3_u32 v36, v37, v36, v52
; DEV float lo2f(u32 w) { return __uint_as_float(w << 16); }
; DEV float hi2f(u32 w) { return __uint_as_float(w & 0xffff0000u); }
; #define MONO_KEY(v_, m_, t_) mono_key((v_), (m_), (t_))
; DEV u32 mono_key(float v, u32 mask, int tag) {
;   u32 u = __float_as_uint(v);
;   u32 k = (u & 0x80000000u) ? ~u : (u | 0x80000000u);
;   return (k & ~mask) | (u32)tag;
; }
; DEV float key_value(u32 k, u32 mask) {
;   k &= ~mask;
;   u32 u = (k & 0x80000000u) ? (k & 0x7fffffffu) : ~k;
;   return __uint_as_float(u);
; }
; __device__ __forceinline__ void ph_peer(const P& p, int l, int nrows, char* smem, int dryc) {
;     ...
; #pragma unroll
;         for (int q = 0; q < 4; q++) {
;           const int c = c0 + q;
;           const u32x4 sv = cur[q];
; #pragma unroll
;           for (int e = 0; e < 4; e++) {
;             KEY_INSERT(MONO_KEY(lo2f(sv[e]), 127u, 127 - (c * 8 + e * 2 + 0)));
;             KEY_INSERT(MONO_KEY(hi2f(sv[e]), 127u, 127 - (c * 8 + e * 2 + 1)));
;           }
;         }
; #pragma unroll
;         for (int q = 0; q < 4; q++) cur[q] = nxt[q];
;       }
	v_med3_u32 v37, v38, v37, v52
	v_med3_u32 v38, v39, v38, v52
	v_med3_u32 v39, v40, v39, v52
	v_med3_u32 v40, v41, v40, v52
	v_med3_u32 v41, v42, v41, v52
	v_med3_u32 v42, v43, v42, v52
	v_med3_u32 v43, v44, v43, v52
	v_med3_u32 v44, v45, v44, v52
	v_med3_u32 v45, v46, v45, v52
	v_med3_u32 v46, v48, v46, v52
	v_med3_u32 v48, v49, v48, v52
	v_med3_u32 v49, v47, v49, v52
	v_max_u32_e32 v47, v47, v52
	v_and_b32_e32 v50, 0xffff0000, v0
	v_ashrrev_i32_e32 v51, 31, v50
	v_or_b32_e32 v51, 0x80000000, v51
	v_xor_b32_e32 v52, v50, v51
	v_and_b32_e32 v52, 0xffffff80, v52
	v_add3_u32 v52, s1, v52, 6
	v_med3_u32 v34, v35, v34, v52
	v_med3_u32 v35, v36, v35, v52
	v_med3_u32 v36, v37, v36, v52
	v_med3_u32 v37, v38, v37, v52
	v_med3_u32 v38, v39, v38, v52
	v_med3_u32 v39, v40, v39, v52
	v_med3_u32 v40, v41, v40, v52
	v_med3_u32 v41, v42, v41, v52
	v_med3_u32 v42, v43, v42, v52
	v_med3_u32 v43, v44, v43, v52
	v_med3_u32 v44, v45, v44, v52
	v_med3_u32 v45, v46, v45, v52
	v_med3_u32 v46, v48, v46, v52
	v_med3_u32 v48, v49, v48, v52
	v_med3_u32 v49, v47, v49, v52
	v_max_u32_e32 v47, v47, v52
	v_lshlrev_b32_e32 v50, 16, v1
	v_ashrrev_i32_e32 v51, 31, v50
	v_or_b32_e32 v51, 0x80000000, v51
	v_xor_b32_e32 v52, v50, v51
	v_and_b32_e32 v52, 0xffffff80, v52
	v_add3_u32 v52, s1, v52, 5
	v_med3_u32 v34, v35, v34, v52
	v_med3_u32 v35, v36, v35, v52
	v_med3_u32 v36, v37, v36, v52
	v_med3_u32 v37, v38, v37, v52
	v_med3_u32 v38, v39, v38, v52
	v_med3_u32 v39, v40, v39, v52
	v_med3_u32 v40, v41, v40, v52
	v_med3_u32 v41, v42, v41, v52
	v_med3_u32 v42, v43, v42, v52
	v_med3_u32 v43, v44, v43, v52
	v_med3_u32 v44, v45, v44, v52
	v_med3_u32 v45, v46, v45, v52
	v_med3_u32 v46, v48, v46, v52
	v_med3_u32 v48, v49, v48, v52
	v_med3_u32 v49, v47, v49, v52
	v_max_u32_e32 v47, v47, v52
	v_and_b32_e32 v50, 0xffff0000, v1
	v_ashrrev_i32_e32 v51, 31, v50
	v_or_b32_e32 v51, 0x80000000, v51
	v_xor_b32_e32 v52, v50, v51
	v_and_b32_e32 v52, 0xffffff80, v52
	v_add3_u32 v52, s1, v52, 4
	v_med3_u32 v34, v35, v34, v52
	v_med3_u32 v35, v36, v35, v52
	v_med3_u32 v36, v37, v36, v52
	v_med3_u32 v37, v38, v37, v52
	v_med3_u32 v38, v39, v38, v52
	v_med3_u32 v39, v40, v39, v52
	v_med3_u32 v40, v41, v40, v52
	v_med3_u32 v41, v42, v41, v52
	v_med3_u32 v42, v43, v42, v52
	v_med3_u32 v43, v44, v43, v52
	v_med3_u32 v44, v45, v44, v52
	v_med3_u32 v45, v46, v45, v52
	v_med3_u32 v46, v48, v46, v52
	v_med3_u32 v48, v49, v48, v52
	v_med3_u32 v49, v47, v49, v52
	v_max_u32_e32 v47, v47, v52
	v_lshlrev_b32_e32 v50, 16, v2
	v_ashrrev_i32_e32 v51, 31, v50
	v_or_b32_e32 v51, 0x80000000, v51
	v_xor_b32_e32 v52, v50, v51
	v_and_b32_e32 v52, 0xffffff80, v52
	v_add3_u32 v52, s1, v52, 3
	v_med3_u32 v34, v35, v34, v52
	v_med3_u32 v35, v36, v35, v52
	v_med3_u32 v36, v37, v36, v52
	v_med3_u32 v37, v38, v37, v52
	v_med3_u32 v38, v39, v38, v52
	v_med3_u32 v39, v40, v39, v52
	v_med3_u32 v40, v41, v40, v52
	v_med3_u32 v41, v42, v41, v52
	v_med3_u32 v42, v43, v42, v52
	v_med3_u32 v43, v44, v43, v52
	v_med3_u32 v44, v45, v44, v52
	v_med3_u32 v45, v46, v45, v52
	v_med3_u32 v46, v48, v46, v52
	v_med3_u32 v48, v49, v48, v52
	v_med3_u32 v49, v47, v49, v52
	v_max_u32_e32 v47, v47, v52
	v_and_b32_e32 v50, 0xffff0000, v2
	v_ashrrev_i32_e32 v51, 31, v50
	v_or_b32_e32 v51, 0x80000000, v51
	v_xor_b32_e32 v52, v50, v51
	v_and_b32_e32 v52, 0xffffff80, v52
	v_add3_u32 v52, s1, v52, 2
	v_med3_u32 v34, v35, v34, v52
	v_med3_u32 v35, v36, v35, v52
	v_med3_u32 v36, v37, v36, v52
	v_med3_u32 v37, v38, v37, v52
	v_med3_u32 v38, v39, v38, v52
	v_med3_u32 v39, v40, v39, v52
	v_med3_u32 v40, v41, v40, v52
	v_med3_u32 v41, v42, v41, v52
	v_med3_u32 v42, v43, v42, v52
	v_med3_u32 v43, v44, v43, v52
	v_med3_u32 v44, v45, v44, v52
	v_med3_u32 v45, v46, v45, v52
	v_med3_u32 v46, v48, v46, v52
	v_med3_u32 v48, v49, v48, v52
	v_med3_u32 v49, v47, v49, v52
	v_max_u32_e32 v47, v47, v52
	v_lshlrev_b32_e32 v50, 16, v3
	v_ashrrev_i32_e32 v51, 31, v50
	v_or_b32_e32 v51, 0x80000000, v51
	v_xor_b32_e32 v52, v50, v51
	v_and_b32_e32 v52, 0xffffff80, v52
	v_add3_u32 v52, s1, v52, 1
	v_med3_u32 v34, v35, v34, v52
	v_med3_u32 v35, v36, v35, v52
	v_med3_u32 v36, v37, v36, v52
	v_med3_u32 v37, v38, v37, v52
	v_med3_u32 v38, v39, v38, v52
	v_med3_u32 v39, v40, v39, v52
	v_med3_u32 v40, v41, v40, v52
	v_med3_u32 v41, v42, v41, v52
	v_med3_u32 v42, v43, v42, v52
	v_med3_u32 v43, v44, v43, v52
	v_med3_u32 v44, v45, v44, v52
	v_med3_u32 v45, v46, v45, v52
	v_med3_u32 v46, v48, v46, v52
	v_med3_u32 v48, v49, v48, v52
	v_med3_u32 v49, v47, v49, v52
	v_max_u32_e32 v47, v47, v52
	v_and_b32_e32 v50, 0xffff0000, v3
	v_ashrrev_i32_e32 v51, 31, v50
	v_or_b32_e32 v51, 0x80000000, v51
	v_xor_b32_e32 v52, v50, v51
	v_and_b32_e32 v52, 0xffffff80, v52
	v_add3_u32 v52, s1, v52, 0
	v_med3_u32 v34, v35, v34, v52
	v_med3_u32 v35, v36, v35, v52
	v_med3_u32 v36, v37, v36, v52
	v_med3_u32 v37, v38, v37, v52
	v_med3_u32 v38, v39, v38, v52
	v_med3_u32 v39, v40, v39, v52
	v_med3_u32 v40, v41, v40, v52
	v_med3_u32 v41, v42, v41, v52
	v_med3_u32 v42, v43, v42, v52
	v_med3_u32 v43, v44, v43, v52
	v_med3_u32 v44, v45, v44, v52
	v_med3_u32 v45, v46, v45, v52
	v_med3_u32 v46, v48, v46, v52
	v_med3_u32 v48, v49, v48, v52
	v_med3_u32 v49, v47, v49, v52
	v_max_u32_e32 v47, v47, v52
	s_sub_i32 s1, s1, 32
	s_and_b64 vcc, exec, s[14:15]
	s_cbranch_vccnz .LBB0_654
	s_waitcnt vmcnt(0)
	v_mov_b64_e32 v[30:31], v[6:7]
	v_mov_b64_e32 v[26:27], v[10:11]
	v_mov_b64_e32 v[22:23], v[14:15]
	v_mov_b64_e32 v[0:1], v[16:17]
	v_mov_b64_e32 v[28:29], v[4:5]
	v_mov_b64_e32 v[24:25], v[8:9]
	v_mov_b64_e32 v[20:21], v[12:13]
	v_mov_b64_e32 v[2:3], v[18:19]
	s_branch .LBB0_650

; DEV f32x4 mfma16(bf16x8 a, bf16x8 b, f32x4 c) { return __builtin_amdgcn_mfma_f32_16x16x32_bf16(a, b, c, 0, 0, 0); }
; template <int HOOK>
; __device__ __forceinline__ void gemm_tile(const u16* __restrict__ A, int lda, const u16* __restrict__ B, int ldb, int K, char* smem, const float* ssq = nullptr) {
;     ...
;     if (HOOK && k0 >= 512 && k0 < 768) {
; #pragma unroll
;       for (int i = 0; i < 4; i++) {
;         float t8[8];
;         unpack8(ra[i], t8);
; #pragma unroll
;         for (int e = 0; e < 8; e++) t8[e] *= rs[i];
;         ra[i] = pack8(t8);
;       }
;     }
;     ...
;     for (int kk = 0; kk < 64; kk += 32) {
;       bf16x8 af[4], bfr[4];
; #pragma unroll
;       for (int i = 0; i < 4; i++) af[i] = *(const bf16x8*)(sA + (wm + i * 16 + lr) * 72 + kk + lq * 8);
; #pragma unroll
;       for (int j = 0; j < 4; j++) bfr[j] = *(const bf16x8*)(sB + (wn + j * 16 + lr) * 72 + kk + lq * 8);
;       __builtin_amdgcn_s_setprio(1);
; #pragma unroll
;       for (int i = 0; i < 4; i++)
; #pragma unroll
;         for (int j = 0; j < 4; j++) acc[i][j] = mfma16(af[i], bfr[j], acc[i][j]);
;       __builtin_amdgcn_s_setprio(0);
;     }
.Ldp5_eh:
	s_waitcnt lgkmcnt(0)
	ds_read_b128 v[176:179], v209 offset:0
	ds_read_b128 v[180:183], v209 offset:2048
	ds_read_b128 v[184:187], v209 offset:4096
	ds_read_b128 v[188:191], v209 offset:6144
	ds_read_b128 v[192:195], v215 offset:16384
	ds_read_b128 v[196:199], v215 offset:18432
	ds_read_b128 v[200:203], v215 offset:20480
	ds_read_b128 v[204:207], v215 offset:22528
	v_lshlrev_b32_e32 v0, 16, v144
	v_and_b32_e32 v1, 0xffff0000, v144
	v_pk_mul_f32 v[0:1], v[96:97], v[0:1]
	v_cvt_pk_bf16_f32 v144, v0, v1
	v_lshlrev_b32_e32 v2, 16, v145
	v_and_b32_e32 v3, 0xffff0000, v145
	v_pk_mul_f32 v[2:3], v[96:97], v[2:3]
	v_cvt_pk_bf16_f32 v145, v2, v3
	v_lshlrev_b32_e32 v4, 16, v146
	v_and_b32_e32 v5, 0xffff0000, v146
	v_pk_mul_f32 v[4:5], v[96:97], v[4:5]
	v_cvt_pk_bf16_f32 v146, v4, v5
	v_lshlrev_b32_e32 v6, 16, v147
	v_and_b32_e32 v7, 0xffff0000, v147
	v_pk_mul_f32 v[6:7], v[96:97], v[6:7]
	v_cvt_pk_bf16_f32 v147, v6, v7
	v_lshlrev_b32_e32 v8, 16, v148
	v_and_b32_e32 v9, 0xffff0000, v148
	v_pk_mul_f32 v[8:9], v[98:99], v[8:9]
	v_cvt_pk_bf16_f32 v148, v8, v9
	v_lshlrev_b32_e32 v10, 16, v149
	v_and_b32_e32 v11, 0xffff0000, v149
	v_pk_mul_f32 v[10:11], v[98:99], v[10:11]
	v_cvt_pk_bf16_f32 v149, v10, v11
	v_lshlrev_b32_e32 v12, 16, v150
	v_and_b32_e32 v13, 0xffff0000, v150
	v_pk_mul_f32 v[12:13], v[98:99], v[12:13]
	v_cvt_pk_bf16_f32 v150, v12, v13
	v_lshlrev_b32_e32 v14, 16, v151
	v_and_b32_e32 v15, 0xffff0000, v151
	v_pk_mul_f32 v[14:15], v[98:99], v[14:15]
	v_cvt_pk_bf16_f32 v151, v14, v15
	v_lshlrev_b32_e32 v0, 16, v152
	v_and_b32_e32 v1, 0xffff0000, v152
	v_pk_mul_f32 v[0:1], v[100:101], v[0:1]
	v_cvt_pk_bf16_f32 v152, v0, v1
	v_lshlrev_b32_e32 v2, 16, v153
	v_and_b32_e32 v3, 0xffff0000, v153
	v_pk_mul_f32 v[2:3], v[100:101], v[2:3]
	v_cvt_pk_bf16_f32 v153, v2, v3
	v_lshlrev_b32_e32 v4, 16, v154
	v_and_b32_e32 v5, 0xffff0000, v154
	v_pk_mul_f32 v[4:5], v[100:101], v[4:5]
	v_cvt_pk_bf16_f32 v154, v4, v5
	v_lshlrev_b32_e32 v6, 16, v155
	v_and_b32_e32 v7, 0xffff0000, v155
	v_pk_mul_f32 v[6:7], v[100:101], v[6:7]
	v_cvt_pk_bf16_f32 v155, v6, v7
	v_lshlrev_b32_e32 v8, 16, v156
	v_and_b32_e32 v9, 0xffff0000, v156
	v_pk_mul_f32 v[8:9], v[102:103], v[8:9]
	v_cvt_pk_bf16_f32 v156, v8, v9
	v_lshlrev_b32_e32 v10, 16, v157
	v_and_b32_e32 v11, 0xffff0000, v157
	v_pk_mul_f32 v[10:11], v[102:103], v[10:11]
	v_cvt_pk_bf16_f32 v157, v10, v11
	v_lshlrev_b32_e32 v12, 16, v158
	v_and_b32_e32 v13, 0xffff0000, v158
	v_pk_mul_f32 v[12:13], v[102:103], v[12:13]
	v_cvt_pk_bf16_f32 v158, v12, v13
	v_lshlrev_b32_e32 v14, 16, v159
	v_and_b32_e32 v15, 0xffff0000, v159
	v_pk_mul_f32 v[14:15], v[102:103], v[14:15]
	v_cvt_pk_bf16_f32 v159, v14, v15
	s_nop 1
	s_setprio 1
	v_mfma_f32_16x16x32_bf16 v[92:95], v[144:147], v[160:163], v[92:95]
	v_lshl_add_u64 v[112:113], v[112:113], 0, s[30:31]
	v_mfma_f32_16x16x32_bf16 v[88:91], v[144:147], v[164:167], v[88:91]
	v_lshl_add_u64 v[114:115], v[114:115], 0, s[30:31]
	v_mfma_f32_16x16x32_bf16 v[84:87], v[144:147], v[168:171], v[84:87]
	v_lshl_add_u64 v[116:117], v[116:117], 0, s[30:31]
	v_mfma_f32_16x16x32_bf16 v[80:83], v[144:147], v[172:175], v[80:83]
	v_lshl_add_u64 v[118:119], v[118:119], 0, s[30:31]
	v_mfma_f32_16x16x32_bf16 v[60:63], v[148:151], v[160:163], v[60:63]
	v_lshl_add_u64 v[120:121], v[120:121], 0, s[30:31]
	v_mfma_f32_16x16x32_bf16 v[56:59], v[148:151], v[164:167], v[56:59]
	v_lshl_add_u64 v[122:123], v[122:123], 0, s[30:31]
	v_mfma_f32_16x16x32_bf16 v[52:55], v[148:151], v[168:171], v[52:55]
	v_lshl_add_u64 v[124:125], v[124:125], 0, s[30:31]
	v_mfma_f32_16x16x32_bf16 v[48:51], v[148:151], v[172:175], v[48:51]
	v_lshl_add_u64 v[126:127], v[126:127], 0, s[30:31]
	v_mfma_f32_16x16x32_bf16 v[44:47], v[152:155], v[160:163], v[44:47]
	v_mfma_f32_16x16x32_bf16 v[40:43], v[152:155], v[164:167], v[40:43]
	v_mfma_f32_16x16x32_bf16 v[36:39], v[152:155], v[168:171], v[36:39]
	v_mfma_f32_16x16x32_bf16 v[32:35], v[152:155], v[172:175], v[32:35]
	v_mfma_f32_16x16x32_bf16 v[64:67], v[156:159], v[160:163], v[64:67]
	v_mfma_f32_16x16x32_bf16 v[68:71], v[156:159], v[164:167], v[68:71]
	v_mfma_f32_16x16x32_bf16 v[72:75], v[156:159], v[168:171], v[72:75]
	v_mfma_f32_16x16x32_bf16 v[76:79], v[156:159], v[172:175], v[76:79]
	s_setprio 0
	s_waitcnt lgkmcnt(0)
; DEV f32x4 mfma16(bf16x8 a, bf16x8 b, f32x4 c) { return __builtin_amdgcn_mfma_f32_16x16x32_bf16(a, b, c, 0, 0, 0); }
; template <int HOOK>
; __device__ __forceinline__ void gemm_tile(const u16* __restrict__ A, int lda, const u16* __restrict__ B, int ldb, int K, char* smem, const float* ssq = nullptr) {
;     ...
;     if (HOOK && k0 >= 512 && k0 < 768) {
; #pragma unroll
;       for (int i = 0; i < 4; i++) {
;         float t8[8];
;         unpack8(ra[i], t8);
; #pragma unroll
;         for (int e = 0; e < 8; e++) t8[e] *= rs[i];
;         ra[i] = pack8(t8);
;       }
;     }
;     ...
;     for (int kk = 0; kk < 64; kk += 32) {
;       bf16x8 af[4], bfr[4];
; #pragma unroll
;       for (int i = 0; i < 4; i++) af[i] = *(const bf16x8*)(sA + (wm + i * 16 + lr) * 72 + kk + lq * 8);
; #pragma unroll
;       for (int j = 0; j < 4; j++) bfr[j] = *(const bf16x8*)(sB + (wn + j * 16 + lr) * 72 + kk + lq * 8);
;       __builtin_amdgcn_s_setprio(1);
; #pragma unroll
;       for (int i = 0; i < 4; i++)
; #pragma unroll
;         for (int j = 0; j < 4; j++) acc[i][j] = mfma16(af[i], bfr[j], acc[i][j]);
;       __builtin_amdgcn_s_setprio(0);
;     }
	v_lshlrev_b32_e32 v0, 16, v176
	v_and_b32_e32 v1, 0xffff0000, v176
	v_pk_mul_f32 v[0:1], v[96:97], v[0:1]
	v_cvt_pk_bf16_f32 v176, v0, v1
	v_lshlrev_b32_e32 v2, 16, v177
	v_and_b32_e32 v3, 0xffff0000, v177
	v_pk_mul_f32 v[2:3], v[96:97], v[2:3]
	v_cvt_pk_bf16_f32 v177, v2, v3
	v_lshlrev_b32_e32 v4, 16, v178
	v_and_b32_e32 v5, 0xffff0000, v178
	v_pk_mul_f32 v[4:5], v[96:97], v[4:5]
	v_cvt_pk_bf16_f32 v178, v4, v5
	v_lshlrev_b32_e32 v6, 16, v179
	v_and_b32_e32 v7, 0xffff0000, v179
	v_pk_mul_f32 v[6:7], v[96:97], v[6:7]
	v_cvt_pk_bf16_f32 v179, v6, v7
	v_lshlrev_b32_e32 v8, 16, v180
	v_and_b32_e32 v9, 0xffff0000, v180
	v_pk_mul_f32 v[8:9], v[98:99], v[8:9]
	v_cvt_pk_bf16_f32 v180, v8, v9
	v_lshlrev_b32_e32 v10, 16, v181
	v_and_b32_e32 v11, 0xffff0000, v181
	v_pk_mul_f32 v[10:11], v[98:99], v[10:11]
	v_cvt_pk_bf16_f32 v181, v10, v11
	v_lshlrev_b32_e32 v12, 16, v182
	v_and_b32_e32 v13, 0xffff0000, v182
	v_pk_mul_f32 v[12:13], v[98:99], v[12:13]
	v_cvt_pk_bf16_f32 v182, v12, v13
	v_lshlrev_b32_e32 v14, 16, v183
	v_and_b32_e32 v15, 0xffff0000, v183
	v_pk_mul_f32 v[14:15], v[98:99], v[14:15]
	v_cvt_pk_bf16_f32 v183, v14, v15
	v_lshlrev_b32_e32 v0, 16, v184
	v_and_b32_e32 v1, 0xffff0000, v184
	v_pk_mul_f32 v[0:1], v[100:101], v[0:1]
	v_cvt_pk_bf16_f32 v184, v0, v1
	v_lshlrev_b32_e32 v2, 16, v185
	v_and_b32_e32 v3, 0xffff0000, v185
	v_pk_mul_f32 v[2:3], v[100:101], v[2:3]
	v_cvt_pk_bf16_f32 v185, v2, v3
	v_lshlrev_b32_e32 v4, 16, v186
	v_and_b32_e32 v5, 0xffff0000, v186
	v_pk_mul_f32 v[4:5], v[100:101], v[4:5]
	v_cvt_pk_bf16_f32 v186, v4, v5
	v_lshlrev_b32_e32 v6, 16, v187
	v_and_b32_e32 v7, 0xffff0000, v187
	v_pk_mul_f32 v[6:7], v[100:101], v[6:7]
	v_cvt_pk_bf16_f32 v187, v6, v7
	v_lshlrev_b32_e32 v8, 16, v188
	v_and_b32_e32 v9, 0xffff0000, v188
	v_pk_mul_f32 v[8:9], v[102:103], v[8:9]
	v_cvt_pk_bf16_f32 v188, v8, v9
	v_lshlrev_b32_e32 v10, 16, v189
	v_and_b32_e32 v11, 0xffff0000, v189
	v_pk_mul_f32 v[10:11], v[102:103], v[10:11]
	v_cvt_pk_bf16_f32 v189, v10, v11
	v_lshlrev_b32_e32 v12, 16, v190
	v_and_b32_e32 v13, 0xffff0000, v190
	v_pk_mul_f32 v[12:13], v[102:103], v[12:13]
	v_cvt_pk_bf16_f32 v190, v12, v13
	v_lshlrev_b32_e32 v14, 16, v191
	v_and_b32_e32 v15, 0xffff0000, v191
	v_pk_mul_f32 v[14:15], v[102:103], v[14:15]
	v_cvt_pk_bf16_f32 v191, v14, v15
	s_nop 1
	s_setprio 1
	v_mfma_f32_16x16x32_bf16 v[92:95], v[176:179], v[192:195], v[92:95]
	v_mfma_f32_16x16x32_bf16 v[88:91], v[176:179], v[196:199], v[88:91]
	v_mfma_f32_16x16x32_bf16 v[84:87], v[176:179], v[200:203], v[84:87]
	v_mfma_f32_16x16x32_bf16 v[80:83], v[176:179], v[204:207], v[80:83]
	v_mfma_f32_16x16x32_bf16 v[60:63], v[180:183], v[192:195], v[60:63]
	v_mfma_f32_16x16x32_bf16 v[56:59], v[180:183], v[196:199], v[56:59]
	v_mfma_f32_16x16x32_bf16 v[52:55], v[180:183], v[200:203], v[52:55]
	v_mfma_f32_16x16x32_bf16 v[48:51], v[180:183], v[204:207], v[48:51]
	v_mfma_f32_16x16x32_bf16 v[44:47], v[184:187], v[192:195], v[44:47]
	v_mfma_f32_16x16x32_bf16 v[40:43], v[184:187], v[196:199], v[40:43]
	v_mfma_f32_16x16x32_bf16 v[36:39], v[184:187], v[200:203], v[36:39]
	v_mfma_f32_16x16x32_bf16 v[32:35], v[184:187], v[204:207], v[32:35]
	v_mfma_f32_16x16x32_bf16 v[64:67], v[188:191], v[192:195], v[64:67]
	v_mfma_f32_16x16x32_bf16 v[68:71], v[188:191], v[196:199], v[68:71]
	v_mfma_f32_16x16x32_bf16 v[72:75], v[188:191], v[200:203], v[72:75]
	v_mfma_f32_16x16x32_bf16 v[76:79], v[188:191], v[204:207], v[76:79]
	s_setprio 0

; DEV f32x4 mfma16(bf16x8 a, bf16x8 b, f32x4 c) { return __builtin_amdgcn_mfma_f32_16x16x32_bf16(a, b, c, 0, 0, 0); }
; template <int HOOK>
; __device__ __forceinline__ void gemm_tile(const u16* __restrict__ A, int lda, const u16* __restrict__ B, int ldb, int K, char* smem, const float* ssq = nullptr) {
;     ...
;     if (HOOK && k0 >= 512 && k0 < 768) {
; #pragma unroll
;       for (int i = 0; i < 4; i++) {
;         float t8[8];
;         unpack8(ra[i], t8);
; #pragma unroll
;         for (int e = 0; e < 8; e++) t8[e] *= rs[i];
;         ra[i] = pack8(t8);
;       }
;     }
;     ...
;     for (int kk = 0; kk < 64; kk += 32) {
;       bf16x8 af[4], bfr[4];
; #pragma unroll
;       for (int i = 0; i < 4; i++) af[i] = *(const bf16x8*)(sA + (wm + i * 16 + lr) * 72 + kk + lq * 8);
; #pragma unroll
;       for (int j = 0; j < 4; j++) bfr[j] = *(const bf16x8*)(sB + (wn + j * 16 + lr) * 72 + kk + lq * 8);
;       __builtin_amdgcn_s_setprio(1);
; #pragma unroll
;       for (int i = 0; i < 4; i++)
; #pragma unroll
;         for (int j = 0; j < 4; j++) acc[i][j] = mfma16(af[i], bfr[j], acc[i][j]);
;       __builtin_amdgcn_s_setprio(0);
;     }
.Ldp5_oh:
	s_waitcnt lgkmcnt(0)
	ds_read_b128 v[176:179], v209 offset:32768
	ds_read_b128 v[180:183], v209 offset:34816
	ds_read_b128 v[184:187], v209 offset:36864
	ds_read_b128 v[188:191], v209 offset:38912
	ds_read_b128 v[192:195], v215 offset:49152
	ds_read_b128 v[196:199], v215 offset:51200
	ds_read_b128 v[200:203], v215 offset:53248
	ds_read_b128 v[204:207], v215 offset:55296
	v_lshlrev_b32_e32 v0, 16, v144
	v_and_b32_e32 v1, 0xffff0000, v144
	v_pk_mul_f32 v[0:1], v[96:97], v[0:1]
	v_cvt_pk_bf16_f32 v144, v0, v1
	v_lshlrev_b32_e32 v2, 16, v145
	v_and_b32_e32 v3, 0xffff0000, v145
	v_pk_mul_f32 v[2:3], v[96:97], v[2:3]
	v_cvt_pk_bf16_f32 v145, v2, v3
	v_lshlrev_b32_e32 v4, 16, v146
	v_and_b32_e32 v5, 0xffff0000, v146
	v_pk_mul_f32 v[4:5], v[96:97], v[4:5]
	v_cvt_pk_bf16_f32 v146, v4, v5
	v_lshlrev_b32_e32 v6, 16, v147
	v_and_b32_e32 v7, 0xffff0000, v147
	v_pk_mul_f32 v[6:7], v[96:97], v[6:7]
	v_cvt_pk_bf16_f32 v147, v6, v7
	v_lshlrev_b32_e32 v8, 16, v148
	v_and_b32_e32 v9, 0xffff0000, v148
	v_pk_mul_f32 v[8:9], v[98:99], v[8:9]
	v_cvt_pk_bf16_f32 v148, v8, v9
	v_lshlrev_b32_e32 v10, 16, v149
	v_and_b32_e32 v11, 0xffff0000, v149
	v_pk_mul_f32 v[10:11], v[98:99], v[10:11]
	v_cvt_pk_bf16_f32 v149, v10, v11
	v_lshlrev_b32_e32 v12, 16, v150
	v_and_b32_e32 v13, 0xffff0000, v150
	v_pk_mul_f32 v[12:13], v[98:99], v[12:13]
	v_cvt_pk_bf16_f32 v150, v12, v13
	v_lshlrev_b32_e32 v14, 16, v151
	v_and_b32_e32 v15, 0xffff0000, v151
	v_pk_mul_f32 v[14:15], v[98:99], v[14:15]
	v_cvt_pk_bf16_f32 v151, v14, v15
	v_lshlrev_b32_e32 v0, 16, v152
	v_and_b32_e32 v1, 0xffff0000, v152
	v_pk_mul_f32 v[0:1], v[100:101], v[0:1]
	v_cvt_pk_bf16_f32 v152, v0, v1
	v_lshlrev_b32_e32 v2, 16, v153
	v_and_b32_e32 v3, 0xffff0000, v153
	v_pk_mul_f32 v[2:3], v[100:101], v[2:3]
	v_cvt_pk_bf16_f32 v153, v2, v3
	v_lshlrev_b32_e32 v4, 16, v154
	v_and_b32_e32 v5, 0xffff0000, v154
	v_pk_mul_f32 v[4:5], v[100:101], v[4:5]
	v_cvt_pk_bf16_f32 v154, v4, v5
	v_lshlrev_b32_e32 v6, 16, v155
	v_and_b32_e32 v7, 0xffff0000, v155
	v_pk_mul_f32 v[6:7], v[100:101], v[6:7]
	v_cvt_pk_bf16_f32 v155, v6, v7
	v_lshlrev_b32_e32 v8, 16, v156
	v_and_b32_e32 v9, 0xffff0000, v156
	v_pk_mul_f32 v[8:9], v[102:103], v[8:9]
	v_cvt_pk_bf16_f32 v156, v8, v9
	v_lshlrev_b32_e32 v10, 16, v157
	v_and_b32_e32 v11, 0xffff0000, v157
	v_pk_mul_f32 v[10:11], v[102:103], v[10:11]
	v_cvt_pk_bf16_f32 v157, v10, v11
	v_lshlrev_b32_e32 v12, 16, v158
	v_and_b32_e32 v13, 0xffff0000, v158
	v_pk_mul_f32 v[12:13], v[102:103], v[12:13]
	v_cvt_pk_bf16_f32 v158, v12, v13
	v_lshlrev_b32_e32 v14, 16, v159
	v_and_b32_e32 v15, 0xffff0000, v159
	v_pk_mul_f32 v[14:15], v[102:103], v[14:15]
	v_cvt_pk_bf16_f32 v159, v14, v15
	s_nop 1
	s_setprio 1
	v_mfma_f32_16x16x32_bf16 v[92:95], v[144:147], v[160:163], v[92:95]
	v_lshl_add_u64 v[112:113], v[112:113], 0, s[30:31]
	v_mfma_f32_16x16x32_bf16 v[88:91], v[144:147], v[164:167], v[88:91]
	v_lshl_add_u64 v[114:115], v[114:115], 0, s[30:31]
	v_mfma_f32_16x16x32_bf16 v[84:87], v[144:147], v[168:171], v[84:87]
	v_lshl_add_u64 v[116:117], v[116:117], 0, s[30:31]
	v_mfma_f32_16x16x32_bf16 v[80:83], v[144:147], v[172:175], v[80:83]
	v_lshl_add_u64 v[118:119], v[118:119], 0, s[30:31]
	v_mfma_f32_16x16x32_bf16 v[60:63], v[148:151], v[160:163], v[60:63]
	v_lshl_add_u64 v[120:121], v[120:121], 0, s[30:31]
	v_mfma_f32_16x16x32_bf16 v[56:59], v[148:151], v[164:167], v[56:59]
	v_lshl_add_u64 v[122:123], v[122:123], 0, s[30:31]
	v_mfma_f32_16x16x32_bf16 v[52:55], v[148:151], v[168:171], v[52:55]
	v_lshl_add_u64 v[124:125], v[124:125], 0, s[30:31]
	v_mfma_f32_16x16x32_bf16 v[48:51], v[148:151], v[172:175], v[48:51]
	v_lshl_add_u64 v[126:127], v[126:127], 0, s[30:31]
	v_mfma_f32_16x16x32_bf16 v[44:47], v[152:155], v[160:163], v[44:47]
	v_mfma_f32_16x16x32_bf16 v[40:43], v[152:155], v[164:167], v[40:43]
	v_mfma_f32_16x16x32_bf16 v[36:39], v[152:155], v[168:171], v[36:39]
	v_mfma_f32_16x16x32_bf16 v[32:35], v[152:155], v[172:175], v[32:35]
	v_mfma_f32_16x16x32_bf16 v[64:67], v[156:159], v[160:163], v[64:67]
	v_mfma_f32_16x16x32_bf16 v[68:71], v[156:159], v[164:167], v[68:71]
	v_mfma_f32_16x16x32_bf16 v[72:75], v[156:159], v[168:171], v[72:75]
	v_mfma_f32_16x16x32_bf16 v[76:79], v[156:159], v[172:175], v[76:79]
	s_setprio 0
	s_waitcnt lgkmcnt(0)
; DEV f32x4 mfma16(bf16x8 a, bf16x8 b, f32x4 c) { return __builtin_amdgcn_mfma_f32_16x16x32_bf16(a, b, c, 0, 0, 0); }
; template <int HOOK>
; __device__ __forceinline__ void gemm_tile(const u16* __restrict__ A, int lda, const u16* __restrict__ B, int ldb, int K, char* smem, const float* ssq = nullptr) {
;     ...
;     if (HOOK && k0 >= 512 && k0 < 768) {
; #pragma unroll
;       for (int i = 0; i < 4; i++) {
;         float t8[8];
;         unpack8(ra[i], t8);
; #pragma unroll
;         for (int e = 0; e < 8; e++) t8[e] *= rs[i];
;         ra[i] = pack8(t8);
;       }
;     }
;     ...
;     for (int kk = 0; kk < 64; kk += 32) {
;       bf16x8 af[4], bfr[4];
; #pragma unroll
;       for (int i = 0; i < 4; i++) af[i] = *(const bf16x8*)(sA + (wm + i * 16 + lr) * 72 + kk + lq * 8);
; #pragma unroll
;       for (int j = 0; j < 4; j++) bfr[j] = *(const bf16x8*)(sB + (wn + j * 16 + lr) * 72 + kk + lq * 8);
;       __builtin_amdgcn_s_setprio(1);
; #pragma unroll
;       for (int i = 0; i < 4; i++)
; #pragma unroll
;         for (int j = 0; j < 4; j++) acc[i][j] = mfma16(af[i], bfr[j], acc[i][j]);
;       __builtin_amdgcn_s_setprio(0);
;     }
	v_lshlrev_b32_e32 v0, 16, v176
	v_and_b32_e32 v1, 0xffff0000, v176
	v_pk_mul_f32 v[0:1], v[96:97], v[0:1]
	v_cvt_pk_bf16_f32 v176, v0, v1
	v_lshlrev_b32_e32 v2, 16, v177
	v_and_b32_e32 v3, 0xffff0000, v177
	v_pk_mul_f32 v[2:3], v[96:97], v[2:3]
	v_cvt_pk_bf16_f32 v177, v2, v3
	v_lshlrev_b32_e32 v4, 16, v178
	v_and_b32_e32 v5, 0xffff0000, v178
	v_pk_mul_f32 v[4:5], v[96:97], v[4:5]
	v_cvt_pk_bf16_f32 v178, v4, v5
	v_lshlrev_b32_e32 v6, 16, v179
	v_and_b32_e32 v7, 0xffff0000, v179
	v_pk_mul_f32 v[6:7], v[96:97], v[6:7]
	v_cvt_pk_bf16_f32 v179, v6, v7
	v_lshlrev_b32_e32 v8, 16, v180
	v_and_b32_e32 v9, 0xffff0000, v180
	v_pk_mul_f32 v[8:9], v[98:99], v[8:9]
	v_cvt_pk_bf16_f32 v180, v8, v9
	v_lshlrev_b32_e32 v10, 16, v181
	v_and_b32_e32 v11, 0xffff0000, v181
	v_pk_mul_f32 v[10:11], v[98:99], v[10:11]
	v_cvt_pk_bf16_f32 v181, v10, v11
	v_lshlrev_b32_e32 v12, 16, v182
	v_and_b32_e32 v13, 0xffff0000, v182
	v_pk_mul_f32 v[12:13], v[98:99], v[12:13]
	v_cvt_pk_bf16_f32 v182, v12, v13
	v_lshlrev_b32_e32 v14, 16, v183
	v_and_b32_e32 v15, 0xffff0000, v183
	v_pk_mul_f32 v[14:15], v[98:99], v[14:15]
	v_cvt_pk_bf16_f32 v183, v14, v15
	v_lshlrev_b32_e32 v0, 16, v184
	v_and_b32_e32 v1, 0xffff0000, v184
	v_pk_mul_f32 v[0:1], v[100:101], v[0:1]
	v_cvt_pk_bf16_f32 v184, v0, v1
	v_lshlrev_b32_e32 v2, 16, v185
	v_and_b32_e32 v3, 0xffff0000, v185
	v_pk_mul_f32 v[2:3], v[100:101], v[2:3]
	v_cvt_pk_bf16_f32 v185, v2, v3
	v_lshlrev_b32_e32 v4, 16, v186
	v_and_b32_e32 v5, 0xffff0000, v186
	v_pk_mul_f32 v[4:5], v[100:101], v[4:5]
	v_cvt_pk_bf16_f32 v186, v4, v5
	v_lshlrev_b32_e32 v6, 16, v187
	v_and_b32_e32 v7, 0xffff0000, v187
	v_pk_mul_f32 v[6:7], v[100:101], v[6:7]
	v_cvt_pk_bf16_f32 v187, v6, v7
	v_lshlrev_b32_e32 v8, 16, v188
	v_and_b32_e32 v9, 0xffff0000, v188
	v_pk_mul_f32 v[8:9], v[102:103], v[8:9]
	v_cvt_pk_bf16_f32 v188, v8, v9
	v_lshlrev_b32_e32 v10, 16, v189
	v_and_b32_e32 v11, 0xffff0000, v189
	v_pk_mul_f32 v[10:11], v[102:103], v[10:11]
	v_cvt_pk_bf16_f32 v189, v10, v11
	v_lshlrev_b32_e32 v12, 16, v190
	v_and_b32_e32 v13, 0xffff0000, v190
	v_pk_mul_f32 v[12:13], v[102:103], v[12:13]
	v_cvt_pk_bf16_f32 v190, v12, v13
	v_lshlrev_b32_e32 v14, 16, v191
	v_and_b32_e32 v15, 0xffff0000, v191
	v_pk_mul_f32 v[14:15], v[102:103], v[14:15]
	v_cvt_pk_bf16_f32 v191, v14, v15
	s_nop 1
	s_setprio 1
	v_mfma_f32_16x16x32_bf16 v[92:95], v[176:179], v[192:195], v[92:95]
	v_mfma_f32_16x16x32_bf16 v[88:91], v[176:179], v[196:199], v[88:91]
	v_mfma_f32_16x16x32_bf16 v[84:87], v[176:179], v[200:203], v[84:87]
	v_mfma_f32_16x16x32_bf16 v[80:83], v[176:179], v[204:207], v[80:83]
	v_mfma_f32_16x16x32_bf16 v[60:63], v[180:183], v[192:195], v[60:63]
	v_mfma_f32_16x16x32_bf16 v[56:59], v[180:183], v[196:199], v[56:59]
	v_mfma_f32_16x16x32_bf16 v[52:55], v[180:183], v[200:203], v[52:55]
	v_mfma_f32_16x16x32_bf16 v[48:51], v[180:183], v[204:207], v[48:51]
	v_mfma_f32_16x16x32_bf16 v[44:47], v[184:187], v[192:195], v[44:47]
	v_mfma_f32_16x16x32_bf16 v[40:43], v[184:187], v[196:199], v[40:43]
	v_mfma_f32_16x16x32_bf16 v[36:39], v[184:187], v[200:203], v[36:39]
	v_mfma_f32_16x16x32_bf16 v[32:35], v[184:187], v[204:207], v[32:35]
	v_mfma_f32_16x16x32_bf16 v[64:67], v[188:191], v[192:195], v[64:67]
	v_mfma_f32_16x16x32_bf16 v[68:71], v[188:191], v[196:199], v[68:71]
	v_mfma_f32_16x16x32_bf16 v[72:75], v[188:191], v[200:203], v[72:75]
	v_mfma_f32_16x16x32_bf16 v[76:79], v[188:191], v[204:207], v[76:79]
	s_setprio 0
